# v074 + next tile's near/cinit scalars evaluated in the PV/exp block, last-tiles handling out of line; two exps per MFMA gap kept, prep work queued one vector op and two scalar ops per gap
# speedup vs baseline: 1.0057x; 1.0057x over previous
; #define ALAS __attribute__((address_space(3)))
; #define AT_DMA(tr) do { const unsigned sb_ = (unsigned)__builtin_amdgcn_readfirstlane(dk + (((tr) & (NSTG - 1)) * STAGE)); const size_t ko_ = (size_t)(tr) * 26 * 4096, vo_ = (size_t)(tr) * 640 * 64; \
;         glds16(kg + ko_, sb_ + OFF_K0); if (!WIN) glds16(kg + ko_ + 4096, sb_ + OFF_K1); glds16(vg + vo_, sb_ + OFF_V); if (!WIN) glds16(vg + vo_ + 64 * 64, sb_ + OFF_V + 8192); } while (0)
; template <bool WIN> ...
;     ...
;         if (tr + 3 < NT) AT_DMA(tr + 3);
;         const int k0 = (t_lo + tr) * 64;
;         const bool skip = WIN && (k0 > qw + 31 + 128 || k0 + 63 < qw - 128);
;         if (!skip) {
;             const bool near = WIN || ((k0 - (qw + 31)) < 128 && (qw - (k0 + 63)) < 128);
;             const float cinit = near ? 0.f : (k0 > qw ? cfar_hi : cfar_lo);
;     ...
;             union PFU { u32x4 u; bf16x8 b; };
;             PFU p0, p1, p2, p3;
;             AT_EXP(s0, 0, p0);
; #pragma unroll
;             for (int kk = 0; kk < 2; ++kk)
; #pragma unroll
;                 for (int db = 0; db < NDB; ++db) vc[kk * NDB + db] = *(const ALAS bf16x8*)(sb + vx[kk + 2] + db * 4096);
;             __builtin_amdgcn_sched_barrier(0);
; #pragma unroll
;             for (int db = 0; db < NDB; ++db) o[db] = __builtin_amdgcn_mfma_f32_32x32x16_bf16(va[db], p0.b, o[db], 0, 0, 0);
;             AT_EXP(s0, 8, p1);
;             __builtin_amdgcn_sched_barrier(0);
; #pragma unroll
;             for (int db = 0; db < NDB; ++db) o[db] = __builtin_amdgcn_mfma_f32_32x32x16_bf16(va[NDB + db], p1.b, o[db], 0, 0, 0);
;             AT_EXP(s1, 0, p2);
;             __builtin_amdgcn_sched_barrier(0);
; #pragma unroll
;             for (int db = 0; db < NDB; ++db) o[db] = __builtin_amdgcn_mfma_f32_32x32x16_bf16(vc[db], p2.b, o[db], 0, 0, 0);
;             AT_EXP(s1, 8, p3);
;             __builtin_amdgcn_sched_barrier(0);
; #pragma unroll
;             for (int db = 0; db < NDB; ++db) o[db] = __builtin_amdgcn_mfma_f32_32x32x16_bf16(vc[NDB + db], p3.b, o[db], 0, 0, 0);
;             __builtin_amdgcn_sched_barrier(0);
;     ...
;             l_run += ls0 + ls1;
.LSPp_pv:
	s_cmp_eq_u32 s86, 0
	s_cbranch_scc1 .LSPp_pure
	s_waitcnt lgkmcnt(4)
	v_mfma_f32_32x32x16_bf16 v[50:65], v[146:149], v[238:241], v[50:65]
	v_exp_f32_e32 v98, v98
	v_exp_f32_e32 v99, v99
	v_mfma_f32_32x32x16_bf16 v[34:49], v[150:153], v[238:241], v[34:49]
	v_exp_f32_e32 v100, v100
	v_exp_f32_e32 v101, v101
	v_mfma_f32_32x32x16_bf16 v[18:33], v[154:157], v[238:241], v[18:33]
	v_exp_f32_e32 v102, v102
	v_exp_f32_e32 v103, v103
	v_add_f32_e32 v228, v98, v100
	v_add_f32_e32 v229, v99, v101
	v_mfma_f32_32x32x16_bf16 v[2:17], v[158:161], v[238:241], v[2:17]
	v_exp_f32_e32 v104, v104
	v_exp_f32_e32 v105, v105
	v_add_f32_e32 v228, v228, v102
	v_add_f32_e32 v229, v229, v103
	v_add3_u32 v236, s99, v183, v187
	ds_read_b128 v[146:149], v236 offset:16384
	ds_read_b128 v[150:153], v236 offset:20480
	ds_read_b128 v[154:157], v236 offset:24576
	ds_read_b128 v[158:161], v236 offset:28672
	s_waitcnt lgkmcnt(4)
	v_mfma_f32_32x32x16_bf16 v[50:65], v[130:133], v[242:245], v[50:65]
	v_exp_f32_e32 v106, v106
	v_exp_f32_e32 v107, v107
	v_add_f32_e32 v228, v228, v104
	v_add_f32_e32 v229, v229, v105
	v_cvt_pk_bf16_f32 v238, v98, v99
	v_lshl_add_u64 v[174:175], v[174:175], 0, s[60:61]
	s_add_i32 s87, s85, 0xffff8000
	s_and_b32 s87, s87, 0x18000
	v_mfma_f32_32x32x16_bf16 v[34:49], v[134:137], v[242:245], v[34:49]
	v_exp_f32_e32 v108, v108
	v_exp_f32_e32 v109, v109
	v_add_f32_e32 v228, v228, v106
	v_add_f32_e32 v229, v229, v107
	v_cvt_pk_bf16_f32 v239, v100, v101
	v_lshl_add_u64 v[172:173], v[172:173], 0, s[48:49]
	s_add_i32 s98, s85, 0x10000
	s_and_b32 s98, s98, 0x18000
	v_mfma_f32_32x32x16_bf16 v[18:33], v[138:141], v[242:245], v[18:33]
	v_exp_f32_e32 v110, v110
	v_exp_f32_e32 v111, v111
	v_add_f32_e32 v228, v228, v108
	v_add_f32_e32 v229, v229, v109
	v_cvt_pk_bf16_f32 v240, v102, v103
	v_lshl_add_u64 v[208:209], v[174:175], 0, s[40:41]
	s_add_i32 s98, s98, s20
	s_add_i32 s101, s85, 0x8000
	v_mfma_f32_32x32x16_bf16 v[2:17], v[142:145], v[242:245], v[2:17]
	v_exp_f32_e32 v112, v112
	v_exp_f32_e32 v113, v113
	v_add_f32_e32 v228, v228, v110
	v_add_f32_e32 v229, v229, v111
	v_cvt_pk_bf16_f32 v241, v104, v105
	v_lshl_add_u64 v[210:211], v[172:173], 0, s[40:41]
	s_and_b32 s101, s101, 0x18000
	s_add_i32 s101, s101, s20
	v_add3_u32 v237, s99, v190, v187
	ds_read_b128 v[130:133], v237 offset:16384
	ds_read_b128 v[134:137], v237 offset:20480
	ds_read_b128 v[138:141], v237 offset:24576
	ds_read_b128 v[142:145], v237 offset:28672
	s_waitcnt lgkmcnt(4)
	v_mfma_f32_32x32x16_bf16 v[50:65], v[146:149], v[246:249], v[50:65]
	v_exp_f32_e32 v82, v82
	v_exp_f32_e32 v83, v83
	v_add_f32_e32 v228, v228, v112
	v_add_f32_e32 v229, v229, v113
	v_cvt_pk_bf16_f32 v242, v106, v107
	v_add3_u32 v212, s87, v178, v162
	s_add_i32 s99, s81, s83
	s_add_i32 s99, s99, 64
	v_mfma_f32_32x32x16_bf16 v[34:49], v[150:153], v[246:249], v[34:49]
	v_exp_f32_e32 v84, v84
	v_exp_f32_e32 v85, v85
	v_add_f32_e32 v228, v228, v82
	v_add_f32_e32 v229, v229, v83
	v_cvt_pk_bf16_f32 v243, v108, v109
	v_add3_u32 v213, s87, v180, v162
	s_sub_i32 m0, s82, 64
	s_max_i32 s99, s99, m0
	v_mfma_f32_32x32x16_bf16 v[18:33], v[154:157], v[246:249], v[18:33]
	v_exp_f32_e32 v86, v86
	v_exp_f32_e32 v87, v87
	v_add_f32_e32 v228, v228, v84
	v_add_f32_e32 v229, v229, v85
	v_cvt_pk_bf16_f32 v244, v110, v111
	v_add3_u32 v214, s87, v182, v162
	s_add_i32 m0, s83, 64
	s_cmp_gt_i32 m0, s78
	v_mfma_f32_32x32x16_bf16 v[2:17], v[158:161], v[246:249], v[2:17]
	v_exp_f32_e32 v88, v88
	v_exp_f32_e32 v89, v89
	v_add_f32_e32 v228, v228, v86
	v_add_f32_e32 v229, v229, v87
	v_cvt_pk_bf16_f32 v245, v112, v113
	v_add3_u32 v215, s87, v184, v162
	s_cselect_b32 m0, s80, s79
	s_cmpk_lt_i32 s99, 0x80
	s_waitcnt lgkmcnt(0)
	v_mfma_f32_32x32x16_bf16 v[50:65], v[130:133], v[250:253], v[50:65]
	v_exp_f32_e32 v90, v90
	v_exp_f32_e32 v91, v91
	v_add_f32_e32 v228, v228, v88
	v_add_f32_e32 v229, v229, v89
	v_cvt_pk_bf16_f32 v246, v82, v83
	s_cselect_b32 s65, 1, 0
	s_cselect_b32 m0, 0, m0
	v_mfma_f32_32x32x16_bf16 v[34:49], v[134:137], v[250:253], v[34:49]
	v_exp_f32_e32 v92, v92
	v_exp_f32_e32 v93, v93
	v_add_f32_e32 v228, v228, v90
	v_add_f32_e32 v229, v229, v91
	v_cvt_pk_bf16_f32 v247, v84, v85
	s_add_i32 s99, s85, 0xffff0000
	s_and_b32 s99, s99, 0x18000
	v_mfma_f32_32x32x16_bf16 v[18:33], v[138:141], v[250:253], v[18:33]
	v_exp_f32_e32 v94, v94
	v_exp_f32_e32 v95, v95
	v_add_f32_e32 v228, v228, v92
	v_add_f32_e32 v229, v229, v93
	v_cvt_pk_bf16_f32 v248, v86, v87
	v_mfma_f32_32x32x16_bf16 v[2:17], v[142:145], v[250:253], v[2:17]
	v_exp_f32_e32 v96, v96
	v_exp_f32_e32 v97, v97
	v_add_f32_e32 v228, v228, v94
	v_add_f32_e32 v229, v229, v95
	v_cvt_pk_bf16_f32 v249, v88, v89
	v_add_f32_e32 v228, v228, v96
	v_add_f32_e32 v229, v229, v97
	v_cvt_pk_bf16_f32 v250, v90, v91
	v_cvt_pk_bf16_f32 v251, v92, v93
	v_cvt_pk_bf16_f32 v252, v94, v95
	v_cvt_pk_bf16_f32 v253, v96, v97
	v_add_f32_e32 v228, v228, v229
	v_cmp_nge_f32_e32 vcc, 0x53800000, v228
	s_cbranch_vccnz .LSPp_redo
	s_add_i32 s86, s86, 1
	s_add_i32 s85, s85, 0x8000
	s_addk_i32 s84, 0x100
	s_add_i32 s83, s83, 64
	s_sub_i32 s82, s82, 64
	v_add_f32_e32 v0, v0, v228
	s_cmpk_eq_u32 s84, 0x8000
	s_cbranch_scc0 .LSPp_top
	s_branch .LSPp_exit

; #define ALAS __attribute__((address_space(3)))
; #define AT_DMA(tr) do { const unsigned sb_ = (unsigned)__builtin_amdgcn_readfirstlane(dk + (((tr) & (NSTG - 1)) * STAGE)); const size_t ko_ = (size_t)(tr) * 26 * 4096, vo_ = (size_t)(tr) * 640 * 64; \
;         glds16(kg + ko_, sb_ + OFF_K0); if (!WIN) glds16(kg + ko_ + 4096, sb_ + OFF_K1); glds16(vg + vo_, sb_ + OFF_V); if (!WIN) glds16(vg + vo_ + 64 * 64, sb_ + OFF_V + 8192); } while (0)
; template <bool WIN> ...
;     ...
;         if (tr + 3 < NT) AT_DMA(tr + 3);
;         const int k0 = (t_lo + tr) * 64;
;         const bool skip = WIN && (k0 > qw + 31 + 128 || k0 + 63 < qw - 128);
;         if (!skip) {
;             const bool near = WIN || ((k0 - (qw + 31)) < 128 && (qw - (k0 + 63)) < 128);
;             const float cinit = near ? 0.f : (k0 > qw ? cfar_hi : cfar_lo);
;     ...
;             union PFU { u32x4 u; bf16x8 b; };
;             PFU p0, p1, p2, p3;
;             AT_EXP(s0, 0, p0);
; #pragma unroll
;             for (int kk = 0; kk < 2; ++kk)
; #pragma unroll
;                 for (int db = 0; db < NDB; ++db) vc[kk * NDB + db] = *(const ALAS bf16x8*)(sb + vx[kk + 2] + db * 4096);
;             __builtin_amdgcn_sched_barrier(0);
; #pragma unroll
;             for (int db = 0; db < NDB; ++db) o[db] = __builtin_amdgcn_mfma_f32_32x32x16_bf16(va[db], p0.b, o[db], 0, 0, 0);
;             AT_EXP(s0, 8, p1);
;             __builtin_amdgcn_sched_barrier(0);
; #pragma unroll
;             for (int db = 0; db < NDB; ++db) o[db] = __builtin_amdgcn_mfma_f32_32x32x16_bf16(va[NDB + db], p1.b, o[db], 0, 0, 0);
;             AT_EXP(s1, 0, p2);
;             __builtin_amdgcn_sched_barrier(0);
; #pragma unroll
;             for (int db = 0; db < NDB; ++db) o[db] = __builtin_amdgcn_mfma_f32_32x32x16_bf16(vc[db], p2.b, o[db], 0, 0, 0);
;             AT_EXP(s1, 8, p3);
;             __builtin_amdgcn_sched_barrier(0);
; #pragma unroll
;             for (int db = 0; db < NDB; ++db) o[db] = __builtin_amdgcn_mfma_f32_32x32x16_bf16(vc[NDB + db], p3.b, o[db], 0, 0, 0);
;             __builtin_amdgcn_sched_barrier(0);
;     ...
;             l_run += ls0 + ls1;
.LSPs_pv:
	s_cmp_eq_u32 s79, 0
	s_cbranch_scc1 .LSPs_pure
	s_waitcnt lgkmcnt(4)
	v_mfma_f32_32x32x16_bf16 v[50:65], v[146:149], v[238:241], v[50:65]
	v_exp_f32_e32 v98, v98
	v_exp_f32_e32 v99, v99
	v_mfma_f32_32x32x16_bf16 v[34:49], v[150:153], v[238:241], v[34:49]
	v_exp_f32_e32 v100, v100
	v_exp_f32_e32 v101, v101
	v_mfma_f32_32x32x16_bf16 v[18:33], v[154:157], v[238:241], v[18:33]
	v_exp_f32_e32 v102, v102
	v_exp_f32_e32 v103, v103
	v_add_f32_e32 v228, v98, v100
	v_add_f32_e32 v229, v99, v101
	v_mfma_f32_32x32x16_bf16 v[2:17], v[158:161], v[238:241], v[2:17]
	v_exp_f32_e32 v104, v104
	v_exp_f32_e32 v105, v105
	v_add_f32_e32 v228, v228, v102
	v_add_f32_e32 v229, v229, v103
	v_add3_u32 v236, s99, v183, v187
	ds_read_b128 v[146:149], v236 offset:16384
	ds_read_b128 v[150:153], v236 offset:20480
	ds_read_b128 v[154:157], v236 offset:24576
	ds_read_b128 v[158:161], v236 offset:28672
	s_waitcnt lgkmcnt(4)
	v_mfma_f32_32x32x16_bf16 v[50:65], v[130:133], v[242:245], v[50:65]
	v_exp_f32_e32 v106, v106
	v_exp_f32_e32 v107, v107
	v_add_f32_e32 v228, v228, v104
	v_add_f32_e32 v229, v229, v105
	v_cvt_pk_bf16_f32 v238, v98, v99
	v_lshl_add_u64 v[174:175], v[174:175], 0, s[60:61]
	s_add_i32 s80, s78, 0xffff8000
	s_and_b32 s80, s80, 0x18000
	v_mfma_f32_32x32x16_bf16 v[34:49], v[134:137], v[242:245], v[34:49]
	v_exp_f32_e32 v108, v108
	v_exp_f32_e32 v109, v109
	v_add_f32_e32 v228, v228, v106
	v_add_f32_e32 v229, v229, v107
	v_cvt_pk_bf16_f32 v239, v100, v101
	v_lshl_add_u64 v[172:173], v[172:173], 0, s[48:49]
	s_add_i32 s98, s78, 0x10000
	s_and_b32 s98, s98, 0x18000
	v_mfma_f32_32x32x16_bf16 v[18:33], v[138:141], v[242:245], v[18:33]
	v_exp_f32_e32 v110, v110
	v_exp_f32_e32 v111, v111
	v_add_f32_e32 v228, v228, v108
	v_add_f32_e32 v229, v229, v109
	v_cvt_pk_bf16_f32 v240, v102, v103
	v_lshl_add_u64 v[208:209], v[174:175], 0, s[40:41]
	s_add_i32 s98, s98, s29
	s_add_i32 s101, s78, 0x8000
	v_mfma_f32_32x32x16_bf16 v[2:17], v[142:145], v[242:245], v[2:17]
	v_exp_f32_e32 v112, v112
	v_exp_f32_e32 v113, v113
	v_add_f32_e32 v228, v228, v110
	v_add_f32_e32 v229, v229, v111
	v_cvt_pk_bf16_f32 v241, v104, v105
	v_lshl_add_u64 v[210:211], v[172:173], 0, s[40:41]
	s_and_b32 s101, s101, 0x18000
	s_add_i32 s101, s101, s29
	v_add3_u32 v237, s99, v190, v187
	ds_read_b128 v[130:133], v237 offset:16384
	ds_read_b128 v[134:137], v237 offset:20480
	ds_read_b128 v[138:141], v237 offset:24576
	ds_read_b128 v[142:145], v237 offset:28672
	s_waitcnt lgkmcnt(4)
	v_mfma_f32_32x32x16_bf16 v[50:65], v[146:149], v[246:249], v[50:65]
	v_exp_f32_e32 v82, v82
	v_exp_f32_e32 v83, v83
	v_add_f32_e32 v228, v228, v112
	v_add_f32_e32 v229, v229, v113
	v_cvt_pk_bf16_f32 v242, v106, v107
	v_add3_u32 v212, s80, v178, v162
	s_add_i32 s99, s76, 64
	s_cmp_gt_u32 s99, s28
	v_mfma_f32_32x32x16_bf16 v[34:49], v[150:153], v[246:249], v[34:49]
	v_exp_f32_e32 v84, v84
	v_exp_f32_e32 v85, v85
	v_add_f32_e32 v228, v228, v82
	v_add_f32_e32 v229, v229, v83
	v_cvt_pk_bf16_f32 v243, v108, v109
	v_add3_u32 v213, s80, v180, v162
	s_cselect_b32 m0, s31, s30
	s_cmp_lt_u32 s99, s33
	v_mfma_f32_32x32x16_bf16 v[18:33], v[154:157], v[246:249], v[18:33]
	v_exp_f32_e32 v86, v86
	v_exp_f32_e32 v87, v87
	v_add_f32_e32 v228, v228, v84
	v_add_f32_e32 v229, v229, v85
	v_cvt_pk_bf16_f32 v244, v110, v111
	v_add3_u32 v214, s80, v182, v162
	s_cselect_b32 s65, 1, 0
	s_cmp_gt_i32 s99, s67
	v_mfma_f32_32x32x16_bf16 v[2:17], v[158:161], v[246:249], v[2:17]
	v_exp_f32_e32 v88, v88
	v_exp_f32_e32 v89, v89
	v_add_f32_e32 v228, v228, v86
	v_add_f32_e32 v229, v229, v87
	v_cvt_pk_bf16_f32 v245, v112, v113
	v_add3_u32 v215, s80, v184, v162
	s_cselect_b32 s65, s65, 0
	s_cmp_lg_u32 s65, 0
	s_waitcnt lgkmcnt(0)
	v_mfma_f32_32x32x16_bf16 v[50:65], v[130:133], v[250:253], v[50:65]
	v_exp_f32_e32 v90, v90
	v_exp_f32_e32 v91, v91
	v_add_f32_e32 v228, v228, v88
	v_add_f32_e32 v229, v229, v89
	v_cvt_pk_bf16_f32 v246, v82, v83
	s_cselect_b32 m0, 0, m0
	s_add_i32 s99, s78, 0xffff0000
	v_mfma_f32_32x32x16_bf16 v[34:49], v[134:137], v[250:253], v[34:49]
	v_exp_f32_e32 v92, v92
	v_exp_f32_e32 v93, v93
	v_add_f32_e32 v228, v228, v90
	v_add_f32_e32 v229, v229, v91
	v_cvt_pk_bf16_f32 v247, v84, v85
	s_and_b32 s99, s99, 0x18000
	v_mfma_f32_32x32x16_bf16 v[18:33], v[138:141], v[250:253], v[18:33]
	v_exp_f32_e32 v94, v94
	v_exp_f32_e32 v95, v95
	v_add_f32_e32 v228, v228, v92
	v_add_f32_e32 v229, v229, v93
	v_cvt_pk_bf16_f32 v248, v86, v87
	v_mfma_f32_32x32x16_bf16 v[2:17], v[142:145], v[250:253], v[2:17]
	v_exp_f32_e32 v96, v96
	v_exp_f32_e32 v97, v97
	v_add_f32_e32 v228, v228, v94
	v_add_f32_e32 v229, v229, v95
	v_cvt_pk_bf16_f32 v249, v88, v89
	v_add_f32_e32 v228, v228, v96
	v_add_f32_e32 v229, v229, v97
	v_cvt_pk_bf16_f32 v250, v90, v91
	v_cvt_pk_bf16_f32 v251, v92, v93
	v_cvt_pk_bf16_f32 v252, v94, v95
	v_cvt_pk_bf16_f32 v253, v96, v97
	v_add_f32_e32 v228, v228, v229
	v_cmp_nge_f32_e32 vcc, 0x53800000, v228
	s_cbranch_vccnz .LSPs_redo
	s_add_i32 s79, s79, 1
	s_add_i32 s78, s78, 0x8000
	s_addk_i32 s77, 0x100
	s_add_i32 s76, s76, 64
	v_add_f32_e32 v0, v0, v228
	s_cmpk_eq_i32 s77, 0x2000
	s_cbranch_scc0 .LSPs_top
	s_branch .LSPs_exit
